# helper tiles of the slow K-prompt workgroups reassigned to the otherwise idle V-sample workgroups
# baseline (speedup 1.0000x reference)
.Lwh_entry:
	s_cmp_lg_u32 s54, 8
	s_cbranch_scc1 .LBB0_664
	s_cmpk_lt_i32 s0, 0x80
	s_cbranch_scc1 .Lwh_go
	s_cmpk_lt_i32 s0, 0x90
	s_cbranch_scc1 .LBB0_664
	s_cmpk_lt_i32 s0, 0xb0
	s_cbranch_scc1 .Lwh_go
	s_sub_i32 s0, s0, 48
.Lwh_go:
	s_mov_b64 exec, -1
	s_waitcnt lgkmcnt(0)
	s_barrier
	s_lshr_b32 s4, s0, 4
	s_and_b32 s5, s0, 15
	s_load_dwordx2 s[24:25], s[72:73], 0xd8
	s_lshl_b32 s28, s4, 20
	s_lshl_b32 s29, s5, 8
	s_add_u32 s28, s28, s29
	s_add_u32 s28, s28, 0x1600000
	s_waitcnt lgkmcnt(0)
	s_add_u32 s24, s24, s28
	s_addc_u32 s25, s25, 0
	v_lshrrev_b32_e32 v40, 4, v156
	v_and_b32_e32 v41, 15, v156
	v_lshlrev_b32_e32 v41, 4, v41
	v_lshl_add_u32 v42, v40, 12, v41
	global_load_dwordx4 v[0:3], v42, s[24:25] nt
	s_add_u32 s24, s24, 0x20000
	s_addc_u32 s25, s25, 0
	global_load_dwordx4 v[4:7], v42, s[24:25] nt
	s_add_u32 s24, s24, 0x20000
	s_addc_u32 s25, s25, 0
	global_load_dwordx4 v[8:11], v42, s[24:25] nt
	s_add_u32 s24, s24, 0x20000
	s_addc_u32 s25, s25, 0
	global_load_dwordx4 v[12:15], v42, s[24:25] nt
	s_add_u32 s24, s24, 0x20000
	s_addc_u32 s25, s25, 0
	global_load_dwordx4 v[16:19], v42, s[24:25] nt
	s_add_u32 s24, s24, 0x20000
	s_addc_u32 s25, s25, 0
	global_load_dwordx4 v[20:23], v42, s[24:25] nt
	s_add_u32 s24, s24, 0x20000
	s_addc_u32 s25, s25, 0
	global_load_dwordx4 v[24:27], v42, s[24:25] nt
	s_add_u32 s24, s24, 0x20000
	s_addc_u32 s25, s25, 0
	global_load_dwordx4 v[28:31], v42, s[24:25] nt
	v_mul_u32_u24_e32 v43, 0x104, v40
	v_add_u32_e32 v43, v43, v41
	s_waitcnt vmcnt(7)
	ds_write2_b32 v43, v0, v1 offset1:1
	ds_write2_b32 v43, v2, v3 offset0:2 offset1:3
	v_add_u32_e32 v43, 0x2080, v43
	s_waitcnt vmcnt(6)
	ds_write2_b32 v43, v4, v5 offset1:1
	ds_write2_b32 v43, v6, v7 offset0:2 offset1:3
	v_add_u32_e32 v43, 0x2080, v43
	s_waitcnt vmcnt(5)
	ds_write2_b32 v43, v8, v9 offset1:1
	ds_write2_b32 v43, v10, v11 offset0:2 offset1:3
	v_add_u32_e32 v43, 0x2080, v43
	s_waitcnt vmcnt(4)
	ds_write2_b32 v43, v12, v13 offset1:1
	ds_write2_b32 v43, v14, v15 offset0:2 offset1:3
	v_add_u32_e32 v43, 0x2080, v43
	s_waitcnt vmcnt(3)
	ds_write2_b32 v43, v16, v17 offset1:1
	ds_write2_b32 v43, v18, v19 offset0:2 offset1:3
	v_add_u32_e32 v43, 0x2080, v43
	s_waitcnt vmcnt(2)
	ds_write2_b32 v43, v20, v21 offset1:1
	ds_write2_b32 v43, v22, v23 offset0:2 offset1:3
	v_add_u32_e32 v43, 0x2080, v43
	s_waitcnt vmcnt(1)
	ds_write2_b32 v43, v24, v25 offset1:1
	ds_write2_b32 v43, v26, v27 offset0:2 offset1:3
	v_add_u32_e32 v43, 0x2080, v43
	s_waitcnt vmcnt(0)
	ds_write2_b32 v43, v28, v29 offset1:1
	ds_write2_b32 v43, v30, v31 offset0:2 offset1:3
	s_waitcnt lgkmcnt(0)
	s_barrier
	v_lshrrev_b32_e32 v40, 3, v156
	v_and_b32_e32 v41, 7, v156
	v_mul_u32_u24_e32 v45, 0x820, v41
	v_lshl_add_u32 v45, v40, 2, v45
	v_and_b32_e32 v46, 32, v40
	v_bfe_u32 v47, v40, 2, 1
	v_lshl_add_u32 v46, v47, 4, v46
	v_bfe_u32 v47, v40, 3, 2
	v_lshl_add_u32 v46, v47, 2, v46
	v_and_b32_e32 v47, 3, v40
	v_add_u32_e32 v46, v46, v47
	v_mul_u32_u24_e32 v46, 0x1600, v46
	v_lshl_add_u32 v46, v41, 4, v46
	s_mul_i32 s28, s5, 0x58000
	s_lshl_b32 s29, s4, 9
	s_add_u32 s28, s28, s29
	s_add_u32 s28, s28, 0x5104000
	s_add_u32 s24, s48, s28
	s_addc_u32 s25, s49, 0
	v_add_u32_e32 v48, 0x0, v45
	ds_read2_b32 v[32:33], v48 offset1:65
	ds_read2_b32 v[34:35], v48 offset0:130 offset1:195
	v_add_u32_e32 v49, 0x410, v48
	ds_read2_b32 v[36:37], v49 offset1:65
	ds_read2_b32 v[38:39], v49 offset0:130 offset1:195
	s_waitcnt lgkmcnt(0)
	v_cvt_pk_bf16_f32 v32, v32, v33
	v_cvt_pk_bf16_f32 v33, v34, v35
	v_cvt_pk_bf16_f32 v34, v36, v37
	v_cvt_pk_bf16_f32 v35, v38, v39
	global_store_dwordx4 v46, v[32:35], s[24:25]
	s_nop 1
	v_add_u32_e32 v48, 0x4100, v45
	ds_read2_b32 v[32:33], v48 offset1:65
	ds_read2_b32 v[34:35], v48 offset0:130 offset1:195
	v_add_u32_e32 v49, 0x410, v48
	ds_read2_b32 v[36:37], v49 offset1:65
	ds_read2_b32 v[38:39], v49 offset0:130 offset1:195
	s_waitcnt lgkmcnt(0)
	v_cvt_pk_bf16_f32 v32, v32, v33
	v_cvt_pk_bf16_f32 v33, v34, v35
	v_cvt_pk_bf16_f32 v34, v36, v37
	v_cvt_pk_bf16_f32 v35, v38, v39
	global_store_dwordx4 v46, v[32:35], s[24:25] offset:128
	s_nop 1
	v_add_u32_e32 v48, 0x8200, v45
	ds_read2_b32 v[32:33], v48 offset1:65
	ds_read2_b32 v[34:35], v48 offset0:130 offset1:195
	v_add_u32_e32 v49, 0x410, v48
	ds_read2_b32 v[36:37], v49 offset1:65
	ds_read2_b32 v[38:39], v49 offset0:130 offset1:195
	s_waitcnt lgkmcnt(0)
	v_cvt_pk_bf16_f32 v32, v32, v33
	v_cvt_pk_bf16_f32 v33, v34, v35
	v_cvt_pk_bf16_f32 v34, v36, v37
	v_cvt_pk_bf16_f32 v35, v38, v39
	global_store_dwordx4 v46, v[32:35], s[24:25] offset:256
	s_nop 1
	v_add_u32_e32 v48, 0xc300, v45
	ds_read2_b32 v[32:33], v48 offset1:65
	ds_read2_b32 v[34:35], v48 offset0:130 offset1:195
	v_add_u32_e32 v49, 0x410, v48
	ds_read2_b32 v[36:37], v49 offset1:65
	ds_read2_b32 v[38:39], v49 offset0:130 offset1:195
	s_waitcnt lgkmcnt(0)
	v_cvt_pk_bf16_f32 v32, v32, v33
	v_cvt_pk_bf16_f32 v33, v34, v35
	v_cvt_pk_bf16_f32 v34, v36, v37
	v_cvt_pk_bf16_f32 v35, v38, v39
	global_store_dwordx4 v46, v[32:35], s[24:25] offset:384
	s_nop 1
	s_barrier
	s_branch .LBB0_664
